# wave 1 of every workgroup issues a speculative L2 writeback at seam arrival so the XCD leader's flush finds less dirty data
# baseline (speedup 1.0000x reference)
.LBB0_800:
	s_getreg_b32 s0, hwreg(HW_REG_XCC_ID, 0, 4)
	s_waitcnt vmcnt(0)
	s_waitcnt vmcnt(0) lgkmcnt(0)
	s_barrier
	s_mov_b64 s[4:5], exec
	v_readlane_b32 s6, v255, 7
	v_readlane_b32 s7, v255, 8
	s_and_b64 s[6:7], s[4:5], s[6:7]
	s_mov_b64 exec, s[6:7]
	s_cbranch_execnz .LBB0_801
	v_readfirstlane_b32 s6, v234
	s_lshr_b32 s6, s6, 6
	s_cmp_lg_u32 s6, 1
	s_cbranch_scc1 .Lseam_skip_wb
	s_mov_b64 exec, 1
	buffer_wbl2 sc1
	s_waitcnt vmcnt(0)
.Lseam_skip_wb:
	s_getpc_b64 s[98:99]
